# grid barrier: XCD leader releases its XCC as soon as the cross-XCC arrival returns and only then waits for its own L1 invalidate (counted vmcnt)
# baseline (speedup 1.0000x reference)
.LBB0_1514:
	s_or_b64 exec, exec, s[12:13]
	buffer_inv sc1
	s_waitcnt vmcnt(1)
	v_readfirstlane_b32 s2, v2
	v_sub_u32_e32 v3, 0, v0
	s_nop 0
	v_add_u32_e32 v2, s2, v1
	v_cvt_f32_u32_e32 v1, v0
	v_rcp_iflag_f32_e32 v1, v1
	s_nop 0
	v_mul_f32_e32 v1, 0x4f7ffffe, v1
	v_cvt_u32_f32_e32 v1, v1
	v_mul_lo_u32 v3, v3, v1
	v_mul_hi_u32 v3, v1, v3
	v_add_u32_e32 v1, v1, v3
	v_mul_hi_u32 v1, v2, v1
	v_mul_lo_u32 v3, v1, v0
	v_sub_u32_e32 v3, v2, v3
	v_cmp_ge_u32_e32 vcc, v3, v0
	v_add_u32_e32 v4, 1, v1
	s_nop 0
	v_cndmask_b32_e32 v1, v1, v4, vcc
	v_sub_u32_e32 v4, v3, v0
	v_cndmask_b32_e32 v3, v3, v4, vcc
	v_cmp_ge_u32_e32 vcc, v3, v0
	v_add_u32_e32 v3, 1, v1
	v_add_u32_e32 v4, 1, v2
	v_cndmask_b32_e32 v1, v1, v3, vcc
	v_mad_u64_u32 v[2:3], s[10:11], v0, v1, v[0:1]
	v_cmp_ne_u32_e32 vcc, v4, v2
	s_and_saveexec_b64 s[10:11], vcc
	s_xor_b64 s[10:11], exec, s[10:11]
	s_cbranch_execz .LBB0_1519
	global_load_dword v0, v153, s[76:77] sc1
	s_waitcnt vmcnt(0)
	v_cmp_eq_u32_e32 vcc, v0, v1
	s_and_saveexec_b64 s[12:13], vcc
	s_cbranch_execz .LBB0_1518
	s_mov_b64 s[14:15], 0

.LBB0_1525:
	s_or_b64 exec, exec, s[12:13]
	s_waitcnt vmcnt(2)
